# P2 row loop: next token row's loads prefetched into a second register set right after the current row's data arrived; counted vmcnt leaves the trip's 7 stores in flight
# speedup vs baseline: 1.0088x; 1.0003x over previous
.LBB0_483:
	s_or_b64 exec, exec, s[0:1]
	v_mov_b32_e32 v70, v0
	s_waitcnt lgkmcnt(0)
	s_barrier
	s_nop 0
	v_readfirstlane_b32 s2, v70
	s_ashr_i32 s0, s2, 6
	s_add_i32 s4, s0, s97
	s_cmp_gt_i32 s4, 0x93ff
	s_cbranch_scc1 .LBB0_502
	v_and_b32_e32 v86, 63, v70
	v_readlane_b32 s44, v253, 60
	v_lshlrev_b32_e32 v88, 4, v86
	v_mov_b32_e32 v89, 0
	v_readlane_b32 s48, v254, 0
	v_readlane_b32 s49, v254, 1
	v_readlane_b32 s50, v254, 2
	v_readlane_b32 s51, v254, 3
	v_lshl_add_u64 v[46:47], s[48:49], 0, v[88:89]
	v_add_co_u32_e32 v26, vcc, 0x1000, v46
	s_nop 0
	global_load_dwordx4 v[2:5], v88, s[48:49] offset:1024
	global_load_dwordx4 v[6:9], v88, s[48:49] offset:2048
	global_load_dwordx4 v[10:13], v88, s[48:49] offset:3072
	v_addc_co_u32_e32 v27, vcc, 0, v47, vcc
	v_add_co_u32_e32 v42, vcc, 0x2000, v46
	global_load_dwordx4 v[14:17], v[26:27], off
	global_load_dwordx4 v[18:21], v[26:27], off offset:1024
	global_load_dwordx4 v[22:25], v[26:27], off offset:2048
	s_nop 0
	global_load_dwordx4 v[26:29], v[26:27], off offset:3072
	v_addc_co_u32_e32 v43, vcc, 0, v47, vcc
	v_add_co_u32_e32 v58, vcc, 0x3000, v46
	global_load_dwordx4 v[30:33], v[42:43], off
	global_load_dwordx4 v[34:37], v[42:43], off offset:1024
	global_load_dwordx4 v[38:41], v[42:43], off offset:2048
	s_nop 0
	global_load_dwordx4 v[42:45], v[42:43], off offset:3072
	v_addc_co_u32_e32 v59, vcc, 0, v47, vcc
	global_load_dwordx4 v[46:49], v[58:59], off
	global_load_dwordx4 v[50:53], v[58:59], off offset:1024
	global_load_dwordx4 v[54:57], v[58:59], off offset:2048
	s_nop 0
	global_load_dwordx4 v[58:61], v[58:59], off offset:3072
	s_nop 0
	global_load_dwordx4 v[62:65], v88, s[48:49]
	global_load_dwordx4 v[66:69], v88, s[50:51]
	v_readlane_b32 s45, v253, 61
	v_readlane_b32 s46, v253, 62
	v_readlane_b32 s47, v253, 63
	v_and_b32_e32 v73, 16, v70
	v_readlane_b32 s16, v254, 12
	v_readlane_b32 s36, v254, 28
	v_lshlrev_b32_e32 v72, 1, v86
	v_cmp_eq_u32_e64 s[8:9], 0, v73
	v_lshlrev_b32_e32 v74, 5, v86
	v_mov_b32_e32 v75, v89
	v_readlane_b32 s17, v254, 13
	v_readlane_b32 s18, v254, 14
	v_readlane_b32 s19, v254, 15
	v_readlane_b32 s20, v254, 16
	v_readlane_b32 s21, v254, 17
	v_readlane_b32 s22, v254, 18
	v_readlane_b32 s23, v254, 19
	v_readlane_b32 s24, v254, 20
	v_readlane_b32 s25, v254, 21
	v_readlane_b32 s26, v254, 22
	v_readlane_b32 s27, v254, 23
	v_readlane_b32 s28, v254, 24
	v_readlane_b32 s29, v254, 25
	v_readlane_b32 s30, v254, 26
	v_readlane_b32 s31, v254, 27
	v_readlane_b32 s37, v254, 29
	v_readlane_b32 s38, v254, 30
	v_readlane_b32 s39, v254, 31
	v_readlane_b32 s40, v254, 32
	v_readlane_b32 s41, v254, 33
	v_readlane_b32 s42, v254, 34
	v_readlane_b32 s43, v254, 35
	v_readlane_b32 s44, v254, 36
	v_readlane_b32 s45, v254, 37
	v_readlane_b32 s46, v254, 38
	v_readlane_b32 s47, v254, 39
	v_readlane_b32 s48, v254, 40
	v_readlane_b32 s49, v254, 41
	v_readlane_b32 s50, v254, 42
	v_readlane_b32 s51, v254, 43
	v_mov_b32_e32 v73, v89
	v_lshl_add_u64 v[92:93], s[22:23], 0, v[74:75]
	v_lshl_add_u64 v[94:95], s[42:43], 0, v[88:89]
	v_lshl_add_u64 v[96:97], s[24:25], 0, v[74:75]
	v_lshl_add_u64 v[98:99], s[44:45], 0, v[88:89]
	v_readlane_b32 s16, v254, 44
	v_lshl_add_u64 v[102:103], s[36:37], 0, v[88:89]
	v_lshl_add_u64 v[104:105], s[38:39], 0, v[88:89]
	v_lshl_add_u64 v[106:107], s[40:41], 0, v[72:73]
	v_readlane_b32 s36, v253, 40
	v_readlane_b32 s17, v254, 45
	v_readlane_b32 s18, v254, 46
	v_readlane_b32 s19, v254, 47
	v_readlane_b32 s20, v254, 48
	v_readlane_b32 s21, v254, 49
	v_readlane_b32 s37, v253, 41
	v_and_b32_e32 v71, 31, v70
	v_readlane_b32 s26, v254, 54
	v_readlane_b32 s27, v254, 55
	v_readlane_b32 s28, v254, 56
	v_readlane_b32 s29, v254, 57
	v_lshlrev_b32_e32 v70, 5, v70
	v_readlane_b32 s38, v253, 42
	v_readlane_b32 s39, v253, 43
	v_readlane_b32 s40, v253, 44
	v_readlane_b32 s41, v253, 45
	v_readlane_b32 s48, v253, 52
	v_readlane_b32 s49, v253, 53
	s_mov_b64 s[16:17], s[36:37]
	v_lshl_add_u64 v[100:101], s[26:27], 0, v[88:89]
	v_and_b32_e32 v88, 0x1e0, v70
	s_mov_b64 s[18:19], s[38:39]
	s_mov_b64 s[28:29], s[48:49]
	v_readlane_b32 s54, v254, 6
	v_readlane_b32 s55, v254, 7
	v_readlane_b32 s56, v254, 8
	v_readlane_b32 s57, v254, 9
	s_bfe_u32 s2, s2, 0x30006
	v_readlane_b32 s24, v254, 52
	v_readlane_b32 s25, v254, 53
	s_mov_b64 s[20:21], s[40:41]
	v_lshl_add_u64 v[108:109], s[28:29], 0, v[88:89]
	v_lshlrev_b32_e32 v88, 2, v71
	s_mov_b32 s18, 0x3d000000
	s_mov_b32 s15, 0
	v_lshlrev_b32_e32 v90, 3, v86
	v_cmp_gt_u32_e64 s[0:1], 48, v86
	v_cmp_gt_u32_e64 s[6:7], 32, v86
	v_and_b32_e32 v87, 30, v72
	s_bitset1_b32 s2, 11
	v_lshl_add_u64 v[110:111], s[54:55], 0, v[74:75]
	v_lshl_add_u64 v[112:113], s[56:57], 0, v[74:75]
	v_lshl_add_u64 v[114:115], s[20:21], 0, v[88:89]
	v_lshl_add_u64 v[116:117], s[24:25], 0, v[74:75]
	v_mov_b32_e32 v118, 0x358637bd
	s_mov_b32 s17, 0x800000
	v_mov_b32_e32 v91, 0xffff
	s_mov_b32 s21, 0xbfb8aa3b
	s_mov_b32 s16, 0xbf317218
	s_mov_b32 s19, 0x3b800000
	v_mov_b32_e32 v119, 0x300
	s_mov_b32 s20, 0x3d800000
	v_readlane_b32 s52, v254, 4
	v_readlane_b32 s53, v254, 5
	v_readlane_b32 s58, v254, 10
	v_readlane_b32 s59, v254, 11
	v_readlane_b32 s22, v254, 50
	v_readlane_b32 s23, v254, 51
	v_readlane_b32 s30, v254, 58
	v_readlane_b32 s31, v254, 59
	v_readlane_b32 s42, v253, 46
	v_readlane_b32 s43, v253, 47
	v_readlane_b32 s44, v253, 48
	v_readlane_b32 s45, v253, 49
	v_readlane_b32 s46, v253, 50
	v_readlane_b32 s47, v253, 51
	v_readlane_b32 s50, v253, 54
	v_readlane_b32 s51, v253, 55
	global_load_dwordx4 v[154:157], v[108:109], off
	global_load_dwordx4 v[158:161], v[108:109], off offset:16
	global_load_dword v152, v[114:115], off
	s_and_saveexec_b64 s[12:13], s[0:1]
	global_load_dwordx4 v[136:139], v[110:111], off
	global_load_dwordx4 v[140:143], v[110:111], off offset:16
	s_and_b64 exec, exec, s[6:7]
	global_load_dwordx4 v[144:147], v[112:113], off
	global_load_dwordx4 v[148:151], v[112:113], off offset:16
	s_mov_b64 exec, s[12:13]
	s_waitcnt vmcnt(0)
	s_mov_b32 s34, 0
	s_branch .LBB0_487

.LBB0_490:
	s_cmp_eq_u32 s34, 1
	s_cbranch_scc0 .Lp2_load
	s_ashr_i32 s5, s4, 31
	s_waitcnt vmcnt(7)
	v_mov_b32_e32 v82, v164
	v_mov_b32_e32 v83, v165
	v_mov_b32_e32 v84, v166
	v_mov_b32_e32 v85, v167
	v_mov_b32_e32 v78, v168
	v_mov_b32_e32 v79, v169
	v_mov_b32_e32 v80, v170
	v_mov_b32_e32 v81, v171
	v_mov_b32_e32 v74, v172
	v_mov_b32_e32 v75, v173
	v_mov_b32_e32 v76, v174
	v_mov_b32_e32 v77, v175
	v_mov_b32_e32 v70, v176
	v_mov_b32_e32 v71, v177
	v_mov_b32_e32 v72, v178
	v_mov_b32_e32 v73, v179
	v_mov_b32_e32 v162, v182
	v_mov_b32_e32 v163, v183
	v_lshlrev_b32_e32 v88, 16, v180
	s_branch .Lp2_have

.Lp2_have:
	s_mov_b32 s34, 0
	s_add_i32 s35, s4, s3
	s_cmp_lt_i32 s35, 0x8400
	s_cbranch_scc0 .Lp2_nopf
	s_mul_i32 s60, s35, 0x1200
	s_mul_hi_i32 s61, s35, 0x1200
	s_add_u32 s60, s74, s60
	s_addc_u32 s61, s75, s61
	global_load_dwordx4 v[164:167], v89, s[60:61] offset:3072
	global_load_dwordx4 v[168:171], v89, s[60:61] offset:3088
	v_mov_b32_e32 v172, 0
	v_mov_b32_e32 v173, 0
	v_mov_b32_e32 v174, 0
	v_mov_b32_e32 v175, 0
	v_mov_b32_e32 v176, 0
	v_mov_b32_e32 v177, 0
	v_mov_b32_e32 v178, 0
	v_mov_b32_e32 v179, 0
	v_mov_b32_e32 v180, 0
	v_lshlrev_b32_e32 v181, 1, v90
	s_and_saveexec_b64 s[62:63], s[0:1]
	global_load_dwordx4 v[172:175], v181, s[60:61] offset:3104
	s_and_b64 exec, exec, s[6:7]
	global_load_dwordx4 v[176:179], v181, s[60:61] offset:3872
	s_ashr_i32 s64, s35, 31
	s_lshr_b32 s65, s64, 21
	s_add_i32 s65, s35, s65
	s_and_b32 s65, s65, 0x7fff800
	s_sub_i32 s65, s35, s65
	s_cmp_lt_i32 s35, 0x8000
	s_cselect_b32 s65, s65, s2
	v_readlane_b32 s66, v253, 7
	v_readlane_b32 s67, v253, 8
	v_lshl_or_b32 v182, s65, 5, v87
	v_ashrrev_i32_e32 v183, 31, v182
	v_lshlrev_b32_e32 v184, 1, v86
	v_mov_b32_e32 v185, 0
	v_lshl_add_u64 v[182:183], v[182:183], 2, s[66:67]
	global_load_dwordx2 v[182:183], v[182:183], off
	v_lshl_add_u64 v[184:185], s[60:61], 0, v[184:185]
	v_add_co_u32_e32 v184, vcc, 0x1000, v184
	s_nop 1
	v_addc_co_u32_e32 v185, vcc, 0, v185, vcc
	global_load_ushort v180, v[184:185], off offset:288
	s_mov_b64 exec, s[62:63]
	s_mov_b32 s34, 1
.Lp2_nopf:
	v_lshlrev_b32_e32 v120, 16, v82
	v_pk_fma_f32 v[124:125], v[64:65], v[120:121], v[68:69] op_sel_hi:[1,0,1]
	v_pk_fma_f32 v[120:121], v[62:63], v[120:121], v[66:67] op_sel_hi:[1,0,1]
	v_lshlrev_b32_e32 v126, 16, v78
	v_pk_fma_f32 v[124:125], v[32:33], v[126:127], v[124:125] op_sel_hi:[1,0,1]
	v_pk_fma_f32 v[120:121], v[30:31], v[126:127], v[120:121] op_sel_hi:[1,0,1]
	v_bfi_b32 v82, v91, 0, v82
	v_pk_fma_f32 v[124:125], v[4:5], v[82:83], v[124:125] op_sel_hi:[1,0,1]
	v_pk_fma_f32 v[120:121], v[2:3], v[82:83], v[120:121] op_sel_hi:[1,0,1]
	v_bfi_b32 v78, v91, 0, v78
	v_pk_fma_f32 v[124:125], v[36:37], v[78:79], v[124:125] op_sel_hi:[1,0,1]
	v_pk_fma_f32 v[120:121], v[34:35], v[78:79], v[120:121] op_sel_hi:[1,0,1]
	v_lshlrev_b32_e32 v78, 16, v83
	v_pk_fma_f32 v[124:125], v[8:9], v[78:79], v[124:125] op_sel_hi:[1,0,1]
	v_pk_fma_f32 v[120:121], v[6:7], v[78:79], v[120:121] op_sel_hi:[1,0,1]
	v_lshlrev_b32_e32 v78, 16, v79
	v_pk_fma_f32 v[124:125], v[40:41], v[78:79], v[124:125] op_sel_hi:[1,0,1]
	v_pk_fma_f32 v[120:121], v[38:39], v[78:79], v[120:121] op_sel_hi:[1,0,1]
	v_bfi_b32 v78, v91, 0, v83
	v_pk_fma_f32 v[82:83], v[12:13], v[78:79], v[124:125] op_sel_hi:[1,0,1]
	v_pk_fma_f32 v[120:121], v[10:11], v[78:79], v[120:121] op_sel_hi:[1,0,1]
	v_bfi_b32 v78, v91, 0, v79
	v_pk_fma_f32 v[82:83], v[44:45], v[78:79], v[82:83] op_sel_hi:[1,0,1]
	v_pk_fma_f32 v[78:79], v[42:43], v[78:79], v[120:121] op_sel_hi:[1,0,1]
	v_lshlrev_b32_e32 v120, 16, v84
	v_pk_fma_f32 v[82:83], v[16:17], v[120:121], v[82:83] op_sel_hi:[1,0,1]
	v_pk_fma_f32 v[78:79], v[14:15], v[120:121], v[78:79] op_sel_hi:[1,0,1]
	v_lshlrev_b32_e32 v120, 16, v80
	v_pk_fma_f32 v[82:83], v[48:49], v[120:121], v[82:83] op_sel_hi:[1,0,1]
	v_pk_fma_f32 v[78:79], v[46:47], v[120:121], v[78:79] op_sel_hi:[1,0,1]
	v_bfi_b32 v84, v91, 0, v84
	v_pk_fma_f32 v[82:83], v[20:21], v[84:85], v[82:83] op_sel_hi:[1,0,1]
	v_pk_fma_f32 v[78:79], v[18:19], v[84:85], v[78:79] op_sel_hi:[1,0,1]
	v_bfi_b32 v80, v91, 0, v80
	v_pk_fma_f32 v[82:83], v[52:53], v[80:81], v[82:83] op_sel_hi:[1,0,1]
	v_pk_fma_f32 v[78:79], v[50:51], v[80:81], v[78:79] op_sel_hi:[1,0,1]
	v_lshlrev_b32_e32 v80, 16, v85
	v_pk_fma_f32 v[82:83], v[24:25], v[80:81], v[82:83] op_sel_hi:[1,0,1]
	v_pk_fma_f32 v[78:79], v[22:23], v[80:81], v[78:79] op_sel_hi:[1,0,1]
	v_lshlrev_b32_e32 v80, 16, v81
	v_pk_fma_f32 v[82:83], v[56:57], v[80:81], v[82:83] op_sel_hi:[1,0,1]
	v_pk_fma_f32 v[78:79], v[54:55], v[80:81], v[78:79] op_sel_hi:[1,0,1]
	v_bfi_b32 v80, v91, 0, v85
	v_pk_fma_f32 v[82:83], v[28:29], v[80:81], v[82:83] op_sel_hi:[1,0,1]
	v_pk_fma_f32 v[78:79], v[26:27], v[80:81], v[78:79] op_sel_hi:[1,0,1]
	v_bfi_b32 v80, v91, 0, v81
	v_pk_fma_f32 v[82:83], v[60:61], v[80:81], v[82:83] op_sel_hi:[1,0,1]
	v_pk_fma_f32 v[78:79], v[58:59], v[80:81], v[78:79] op_sel_hi:[1,0,1]
	v_min_f32_e32 v84, 0, v82
	v_min_f32_e32 v80, 0, v78
	v_mul_f32_e64 v78, |v78|, s21
	v_min_f32_e32 v81, 0, v79
	v_mul_f32_e64 v79, |v79|, s21
	v_mul_f32_e64 v82, |v82|, s21
	v_min_f32_e32 v85, 0, v83
	v_mul_f32_e64 v83, |v83|, s21
	v_exp_f32_e32 v78, v78
	v_exp_f32_e32 v79, v79
	v_exp_f32_e32 v82, v82
	v_exp_f32_e32 v83, v83
	v_add_f32_e32 v78, 1.0, v78
	v_add_f32_e32 v79, 1.0, v79
	v_add_f32_e32 v82, 1.0, v82
	v_add_f32_e32 v83, 1.0, v83
	v_log_f32_e32 v78, v78
	v_log_f32_e32 v79, v79
	v_log_f32_e32 v82, v82
	v_log_f32_e32 v83, v83
	s_lshl_b64 s[10:11], s[4:5], 10
	v_pk_fma_f32 v[78:79], v[78:79], s[16:17], v[80:81] op_sel_hi:[1,0,1]
	v_pk_fma_f32 v[82:83], v[82:83], s[16:17], v[84:85] op_sel_hi:[1,0,1]
	s_nop 0
	v_pk_mul_f32 v[80:81], v[82:83], s[20:21] op_sel_hi:[1,0]
	v_pk_mul_f32 v[78:79], v[78:79], s[20:21] op_sel_hi:[1,0]
	v_lshl_add_u64 v[82:83], v[100:101], 0, s[10:11]
	global_store_dwordx4 v[82:83], v[78:81], off
	v_and_b32_e32 v83, 0xffff0000, v75
	v_lshlrev_b32_e32 v82, 16, v75
	v_and_b32_e32 v79, 0xffff0000, v70
	v_lshlrev_b32_e32 v78, 16, v70
	v_mul_f32_e32 v70, v79, v79
	v_and_b32_e32 v81, 0xffff0000, v74
	v_lshlrev_b32_e32 v80, 16, v74
	v_pk_fma_f32 v[84:85], v[78:79], v[78:79], v[70:71] op_sel_hi:[1,1,0]
	v_and_b32_e32 v75, 0xffff0000, v71
	v_lshlrev_b32_e32 v74, 16, v71
	v_pk_fma_f32 v[70:71], v[74:75], v[74:75], v[84:85]
	v_mul_f32_e32 v84, v75, v75
	v_pk_add_f32 v[120:121], v[84:85], v[70:71] op_sel_hi:[0,1]
	v_and_b32_e32 v71, 0xffff0000, v72
	v_lshlrev_b32_e32 v70, 16, v72
	v_pk_mul_f32 v[124:125], v[80:81], v[80:81]
	v_pk_fma_f32 v[120:121], v[70:71], v[70:71], v[120:121]
	v_mul_f32_e32 v72, v71, v71
	v_pk_mul_f32 v[126:127], v[82:83], v[82:83]
	v_pk_add_f32 v[130:131], v[72:73], v[120:121] op_sel_hi:[0,1]
	v_add_f32_e32 v72, v124, v125
	v_and_b32_e32 v85, 0xffff0000, v76
	v_lshlrev_b32_e32 v84, 16, v76
	v_add_f32_e32 v72, v126, v72
	v_pk_mul_f32 v[128:129], v[84:85], v[84:85]
	v_add_f32_e32 v72, v127, v72
	v_and_b32_e32 v121, 0xffff0000, v77
	v_lshlrev_b32_e32 v120, 16, v77
	v_add_f32_e32 v72, v128, v72
	v_pk_mul_f32 v[132:133], v[120:121], v[120:121]
	v_add_f32_e32 v72, v129, v72
	v_and_b32_e32 v77, 0xffff0000, v73
	v_lshlrev_b32_e32 v76, 16, v73
	v_add_f32_e32 v72, v132, v72
	v_add_f32_e32 v123, v133, v72
	v_pk_fma_f32 v[72:73], v[76:77], v[76:77], v[130:131]
	v_mul_f32_e32 v124, v77, v77
	v_pk_add_f32 v[72:73], v[124:125], v[72:73] op_sel_hi:[0,1]
	v_mov_b32_e32 v73, v72
	v_mul_f32_e32 v72, v88, v88
	v_xor_b32_e32 v124, 16, v122
	v_lshlrev_b32_e32 v124, 2, v124
	v_add_f32_dpp v123, v123, v123 quad_perm:[1,0,3,2] row_mask:0xf bank_mask:0xf
	v_add_f32_dpp v72, v72, v72 quad_perm:[1,0,3,2] row_mask:0xf bank_mask:0xf
	v_add_f32_dpp v73, v73, v73 quad_perm:[1,0,3,2] row_mask:0xf bank_mask:0xf
	v_add_f32_dpp v123, v123, v123 quad_perm:[2,3,0,1] row_mask:0xf bank_mask:0xf
	v_add_f32_dpp v72, v72, v72 quad_perm:[2,3,0,1] row_mask:0xf bank_mask:0xf
	v_add_f32_dpp v73, v73, v73 quad_perm:[2,3,0,1] row_mask:0xf bank_mask:0xf
	v_add_f32_dpp v123, v123, v123 row_half_mirror row_mask:0xf bank_mask:0xf
	v_add_f32_dpp v72, v72, v72 row_half_mirror row_mask:0xf bank_mask:0xf
	v_add_f32_dpp v73, v73, v73 row_half_mirror row_mask:0xf bank_mask:0xf
	v_add_f32_dpp v123, v123, v123 row_mirror row_mask:0xf bank_mask:0xf
	v_add_f32_dpp v72, v72, v72 row_mirror row_mask:0xf bank_mask:0xf
	v_add_f32_dpp v73, v73, v73 row_mirror row_mask:0xf bank_mask:0xf
	v_mov_b32_e32 v125, v123
	v_mov_b32_e32 v126, v72
	v_mov_b32_e32 v127, v73
	v_permlane16_swap_b32_e32 v123, v125
	v_permlane16_swap_b32_e32 v72, v126
	v_permlane16_swap_b32_e32 v73, v127
	v_add_f32_e32 v123, v123, v125
	v_add_f32_e32 v72, v72, v126
	v_add_f32_e32 v73, v73, v127
	v_mov_b32_e32 v125, v123
	v_mov_b32_e32 v126, v72
	v_mov_b32_e32 v127, v73
	v_permlane32_swap_b32_e32 v123, v125
	v_permlane32_swap_b32_e32 v72, v126
	v_permlane32_swap_b32_e32 v73, v127
	v_add_f32_e32 v123, v123, v125
	v_add_f32_e32 v72, v72, v126
	v_add_f32_e32 v73, v73, v127
	v_mov_b32_e32 v125, v123
	v_mov_b32_e32 v126, 0
	v_mov_b32_e32 v122, 0
	v_mov_b32_e32 v123, 0
	s_and_saveexec_b64 s[12:13], s[0:1]
	s_cbranch_execz .LBB0_498
	v_add_f32_e32 v125, v125, v126
	v_fmamk_f32 v125, v125, 0x3b2aaaab, v118
	v_mul_f32_e32 v126, 0x4b800000, v125
	v_cmp_gt_f32_e32 vcc, s17, v125
	s_nop 1
	v_cndmask_b32_e32 v125, v125, v126, vcc
	v_rsq_f32_e32 v125, v125
	s_nop 0
	v_mul_f32_e32 v126, 0x45800000, v125
	v_cndmask_b32_e32 v126, v125, v126, vcc
	v_pk_mul_f32 v[80:81], v[126:127], v[80:81] op_sel_hi:[0,1]
	v_pk_mul_f32 v[82:83], v[126:127], v[82:83] op_sel_hi:[0,1]
	v_pk_mul_f32 v[84:85], v[126:127], v[84:85] op_sel_hi:[0,1]
	v_pk_mul_f32 v[120:121], v[126:127], v[120:121] op_sel_hi:[0,1]
	v_pk_mul_f32 v[80:81], v[80:81], v[136:137]
	v_pk_mul_f32 v[82:83], v[82:83], v[138:139]
	v_pk_mul_f32 v[84:85], v[84:85], v[140:141]
	v_pk_mul_f32 v[120:121], v[120:121], v[142:143]
	v_cvt_pk_bf16_f32 v80, v80, v81
	v_cvt_pk_bf16_f32 v81, v82, v83
	v_cvt_pk_bf16_f32 v82, v84, v85
	v_cvt_pk_bf16_f32 v83, v120, v121
	v_mad_i64_i32 v[84:85], s[10:11], s4, v119, v[102:103]
	global_store_dwordx4 v[84:85], v[80:83], off
